# speedup vs baseline: 1.0863x; 1.0059x over previous
.LBB0_381:
	s_waitcnt vmcnt(0)
	v_mov_b32_e32 v78, v208
	v_mov_b32_e32 v79, v209
	v_mov_b32_e32 v80, v210
	v_mov_b32_e32 v81, v211
	v_mov_b32_e32 v74, v212
	v_mov_b32_e32 v75, v213
	v_mov_b32_e32 v76, v214
	v_mov_b32_e32 v77, v215
	v_mov_b32_e32 v70, v216
	v_mov_b32_e32 v71, v217
	v_mov_b32_e32 v72, v218
	v_mov_b32_e32 v73, v219
	v_mov_b32_e32 v66, v220
	v_mov_b32_e32 v67, v221
	v_mov_b32_e32 v68, v222
	v_mov_b32_e32 v69, v223
	s_add_i32 s0, s1, 4
	s_add_i32 s12, s1, 5
	s_min_u32 s14, s0, 27
	s_add_i32 s13, s1, 6
	s_min_u32 s12, s12, 27
	s_lshl_b32 s14, s14, 9
	s_add_i32 s1, s1, 7
	s_min_u32 s13, s13, 27
	v_lshl_add_u64 v[158:159], v[124:125], 0, s[14:15]
	s_lshl_b32 s14, s12, 9
	s_min_u32 s40, s1, 27
	v_lshl_add_u64 v[162:163], v[158:159], 0, s[30:31]
	v_lshl_add_u64 v[158:159], v[124:125], 0, s[14:15]
	s_lshl_b32 s14, s13, 9
	v_lshl_add_u64 v[160:161], v[124:125], 0, s[14:15]
	s_lshl_b32 s14, s40, 9
	s_mov_b32 s1, s0
	v_lshl_add_u64 v[158:159], v[158:159], 0, s[30:31]
	v_lshl_add_u64 v[160:161], v[160:161], 0, s[30:31]
	v_lshl_add_u64 v[224:225], v[124:125], 0, s[14:15]
	v_lshl_add_u64 v[224:225], v[224:225], 0, s[30:31]
	global_load_dwordx4 v[208:211], v[162:163], off
	global_load_dwordx4 v[212:215], v[158:159], off
	global_load_dwordx4 v[216:219], v[160:161], off
	global_load_dwordx4 v[220:223], v[224:225], off
	s_cmp_lt_u32 s0, 28
	v_pk_mul_f32 v[200:201], v[154:155], v[62:63]
	v_pk_mul_f32 v[202:203], v[120:121], v[64:65]
	v_pk_fma_f32 v[62:63], v[156:157], v[62:63], v[200:201] op_sel:[0,1,0] op_sel_hi:[1,0,1] neg_lo:[1,0,0]
	v_pk_fma_f32 v[64:65], v[122:123], v[64:65], v[202:203] op_sel:[0,1,0] op_sel_hi:[1,0,1] neg_lo:[1,0,0]
	v_pk_mul_f32 v[204:205], v[150:151], v[58:59]
	v_pk_mul_f32 v[206:207], v[116:117], v[60:61]
	v_pk_fma_f32 v[58:59], v[152:153], v[58:59], v[204:205] op_sel:[0,1,0] op_sel_hi:[1,0,1] neg_lo:[1,0,0]
	v_pk_fma_f32 v[60:61], v[118:119], v[60:61], v[206:207] op_sel:[0,1,0] op_sel_hi:[1,0,1] neg_lo:[1,0,0]
	v_mfma_f32_16x16x32_bf16 v[62:65], v[34:37], v[78:81], v[62:65]
	v_pk_mul_f32 v[200:201], v[146:147], v[54:55]
	v_pk_mul_f32 v[202:203], v[112:113], v[56:57]
	v_pk_fma_f32 v[54:55], v[148:149], v[54:55], v[200:201] op_sel:[0,1,0] op_sel_hi:[1,0,1] neg_lo:[1,0,0]
	v_pk_fma_f32 v[56:57], v[114:115], v[56:57], v[202:203] op_sel:[0,1,0] op_sel_hi:[1,0,1] neg_lo:[1,0,0]
	v_mfma_f32_16x16x32_bf16 v[58:61], v[26:29], v[78:81], v[58:61]
	v_pk_mul_f32 v[204:205], v[142:143], v[18:19]
	v_pk_mul_f32 v[206:207], v[108:109], v[20:21]
	v_pk_fma_f32 v[18:19], v[144:145], v[18:19], v[204:205] op_sel:[0,1,0] op_sel_hi:[1,0,1] neg_lo:[1,0,0]
	v_pk_fma_f32 v[20:21], v[110:111], v[20:21], v[206:207] op_sel:[0,1,0] op_sel_hi:[1,0,1] neg_lo:[1,0,0]
	v_mfma_f32_16x16x32_bf16 v[54:57], v[30:33], v[78:81], v[54:57]
	v_pk_mul_f32 v[200:201], v[130:131], v[14:15]
	v_pk_mul_f32 v[202:203], v[96:97], v[16:17]
	v_pk_fma_f32 v[14:15], v[140:141], v[14:15], v[200:201] op_sel:[0,1,0] op_sel_hi:[1,0,1] neg_lo:[1,0,0]
	v_pk_fma_f32 v[16:17], v[106:107], v[16:17], v[202:203] op_sel:[0,1,0] op_sel_hi:[1,0,1] neg_lo:[1,0,0]
	v_mfma_f32_16x16x32_bf16 v[18:21], v[22:25], v[78:81], v[18:21]
	v_pk_mul_f32 v[204:205], v[128:129], v[10:11]
	v_pk_mul_f32 v[206:207], v[94:95], v[12:13]
	v_pk_fma_f32 v[10:11], v[138:139], v[10:11], v[204:205] op_sel:[0,1,0] op_sel_hi:[1,0,1] neg_lo:[1,0,0]
	v_pk_fma_f32 v[12:13], v[104:105], v[12:13], v[206:207] op_sel:[0,1,0] op_sel_hi:[1,0,1] neg_lo:[1,0,0]
	v_mfma_f32_16x16x32_bf16 v[14:17], v[38:41], v[78:81], v[14:17]
	v_pk_mul_f32 v[200:201], v[126:127], v[6:7]
	v_pk_mul_f32 v[202:203], v[92:93], v[8:9]
	v_pk_fma_f32 v[6:7], v[136:137], v[6:7], v[200:201] op_sel:[0,1,0] op_sel_hi:[1,0,1] neg_lo:[1,0,0]
	v_pk_fma_f32 v[8:9], v[102:103], v[8:9], v[202:203] op_sel:[0,1,0] op_sel_hi:[1,0,1] neg_lo:[1,0,0]
	v_mfma_f32_16x16x32_bf16 v[10:13], v[42:45], v[78:81], v[10:13]
	v_pk_mul_f32 v[204:205], v[132:133], v[2:3]
	v_pk_mul_f32 v[206:207], v[98:99], v[4:5]
	v_pk_fma_f32 v[2:3], v[134:135], v[2:3], v[204:205] op_sel:[0,1,0] op_sel_hi:[1,0,1] neg_lo:[1,0,0]
	v_pk_fma_f32 v[4:5], v[100:101], v[4:5], v[206:207] op_sel:[0,1,0] op_sel_hi:[1,0,1] neg_lo:[1,0,0]
	v_mfma_f32_16x16x32_bf16 v[6:9], v[46:49], v[78:81], v[6:9]
	s_nop 1
	v_mfma_f32_16x16x32_bf16 v[2:5], v[50:53], v[78:81], v[2:5]
	v_pk_mul_f32 v[200:201], v[154:155], v[62:63]
	v_pk_mul_f32 v[202:203], v[120:121], v[64:65]
	v_pk_fma_f32 v[62:63], v[156:157], v[62:63], v[200:201] op_sel:[0,1,0] op_sel_hi:[1,0,1] neg_lo:[1,0,0]
	v_pk_fma_f32 v[64:65], v[122:123], v[64:65], v[202:203] op_sel:[0,1,0] op_sel_hi:[1,0,1] neg_lo:[1,0,0]
	v_pk_mul_f32 v[204:205], v[150:151], v[58:59]
	v_pk_mul_f32 v[206:207], v[116:117], v[60:61]
	v_pk_fma_f32 v[58:59], v[152:153], v[58:59], v[204:205] op_sel:[0,1,0] op_sel_hi:[1,0,1] neg_lo:[1,0,0]
	v_pk_fma_f32 v[60:61], v[118:119], v[60:61], v[206:207] op_sel:[0,1,0] op_sel_hi:[1,0,1] neg_lo:[1,0,0]
	v_mfma_f32_16x16x32_bf16 v[62:65], v[34:37], v[74:77], v[62:65]
	v_pk_mul_f32 v[200:201], v[146:147], v[54:55]
	v_pk_mul_f32 v[202:203], v[112:113], v[56:57]
	v_pk_fma_f32 v[54:55], v[148:149], v[54:55], v[200:201] op_sel:[0,1,0] op_sel_hi:[1,0,1] neg_lo:[1,0,0]
	v_pk_fma_f32 v[56:57], v[114:115], v[56:57], v[202:203] op_sel:[0,1,0] op_sel_hi:[1,0,1] neg_lo:[1,0,0]
	v_mfma_f32_16x16x32_bf16 v[58:61], v[26:29], v[74:77], v[58:61]
	v_pk_mul_f32 v[204:205], v[142:143], v[18:19]
	v_pk_mul_f32 v[206:207], v[108:109], v[20:21]
	v_pk_fma_f32 v[18:19], v[144:145], v[18:19], v[204:205] op_sel:[0,1,0] op_sel_hi:[1,0,1] neg_lo:[1,0,0]
	v_pk_fma_f32 v[20:21], v[110:111], v[20:21], v[206:207] op_sel:[0,1,0] op_sel_hi:[1,0,1] neg_lo:[1,0,0]
	v_mfma_f32_16x16x32_bf16 v[54:57], v[30:33], v[74:77], v[54:57]
	v_pk_mul_f32 v[200:201], v[130:131], v[14:15]
	v_pk_mul_f32 v[202:203], v[96:97], v[16:17]
	v_pk_fma_f32 v[14:15], v[140:141], v[14:15], v[200:201] op_sel:[0,1,0] op_sel_hi:[1,0,1] neg_lo:[1,0,0]
	v_pk_fma_f32 v[16:17], v[106:107], v[16:17], v[202:203] op_sel:[0,1,0] op_sel_hi:[1,0,1] neg_lo:[1,0,0]
	v_mfma_f32_16x16x32_bf16 v[18:21], v[22:25], v[74:77], v[18:21]
	v_pk_mul_f32 v[204:205], v[128:129], v[10:11]
	v_pk_mul_f32 v[206:207], v[94:95], v[12:13]
	v_pk_fma_f32 v[10:11], v[138:139], v[10:11], v[204:205] op_sel:[0,1,0] op_sel_hi:[1,0,1] neg_lo:[1,0,0]
	v_pk_fma_f32 v[12:13], v[104:105], v[12:13], v[206:207] op_sel:[0,1,0] op_sel_hi:[1,0,1] neg_lo:[1,0,0]
	v_mfma_f32_16x16x32_bf16 v[14:17], v[38:41], v[74:77], v[14:17]
	v_pk_mul_f32 v[200:201], v[126:127], v[6:7]
	v_pk_mul_f32 v[202:203], v[92:93], v[8:9]
	v_pk_fma_f32 v[6:7], v[136:137], v[6:7], v[200:201] op_sel:[0,1,0] op_sel_hi:[1,0,1] neg_lo:[1,0,0]
	v_pk_fma_f32 v[8:9], v[102:103], v[8:9], v[202:203] op_sel:[0,1,0] op_sel_hi:[1,0,1] neg_lo:[1,0,0]
	v_mfma_f32_16x16x32_bf16 v[10:13], v[42:45], v[74:77], v[10:13]
	v_pk_mul_f32 v[204:205], v[132:133], v[2:3]
	v_pk_mul_f32 v[206:207], v[98:99], v[4:5]
	v_pk_fma_f32 v[2:3], v[134:135], v[2:3], v[204:205] op_sel:[0,1,0] op_sel_hi:[1,0,1] neg_lo:[1,0,0]
	v_pk_fma_f32 v[4:5], v[100:101], v[4:5], v[206:207] op_sel:[0,1,0] op_sel_hi:[1,0,1] neg_lo:[1,0,0]
	v_mfma_f32_16x16x32_bf16 v[6:9], v[46:49], v[74:77], v[6:9]
	s_nop 1
	v_mfma_f32_16x16x32_bf16 v[2:5], v[50:53], v[74:77], v[2:5]
	v_pk_mul_f32 v[200:201], v[154:155], v[62:63]
	v_pk_mul_f32 v[202:203], v[120:121], v[64:65]
	v_pk_fma_f32 v[62:63], v[156:157], v[62:63], v[200:201] op_sel:[0,1,0] op_sel_hi:[1,0,1] neg_lo:[1,0,0]
	v_pk_fma_f32 v[64:65], v[122:123], v[64:65], v[202:203] op_sel:[0,1,0] op_sel_hi:[1,0,1] neg_lo:[1,0,0]
	v_pk_mul_f32 v[204:205], v[150:151], v[58:59]
	v_pk_mul_f32 v[206:207], v[116:117], v[60:61]
	v_pk_fma_f32 v[58:59], v[152:153], v[58:59], v[204:205] op_sel:[0,1,0] op_sel_hi:[1,0,1] neg_lo:[1,0,0]
	v_pk_fma_f32 v[60:61], v[118:119], v[60:61], v[206:207] op_sel:[0,1,0] op_sel_hi:[1,0,1] neg_lo:[1,0,0]
	v_mfma_f32_16x16x32_bf16 v[62:65], v[34:37], v[70:73], v[62:65]
	v_pk_mul_f32 v[200:201], v[146:147], v[54:55]
	v_pk_mul_f32 v[202:203], v[112:113], v[56:57]
	v_pk_fma_f32 v[54:55], v[148:149], v[54:55], v[200:201] op_sel:[0,1,0] op_sel_hi:[1,0,1] neg_lo:[1,0,0]
	v_pk_fma_f32 v[56:57], v[114:115], v[56:57], v[202:203] op_sel:[0,1,0] op_sel_hi:[1,0,1] neg_lo:[1,0,0]
	v_mfma_f32_16x16x32_bf16 v[58:61], v[26:29], v[70:73], v[58:61]
	v_pk_mul_f32 v[204:205], v[142:143], v[18:19]
	v_pk_mul_f32 v[206:207], v[108:109], v[20:21]
	v_pk_fma_f32 v[18:19], v[144:145], v[18:19], v[204:205] op_sel:[0,1,0] op_sel_hi:[1,0,1] neg_lo:[1,0,0]
	v_pk_fma_f32 v[20:21], v[110:111], v[20:21], v[206:207] op_sel:[0,1,0] op_sel_hi:[1,0,1] neg_lo:[1,0,0]
	v_mfma_f32_16x16x32_bf16 v[54:57], v[30:33], v[70:73], v[54:57]
	v_pk_mul_f32 v[200:201], v[130:131], v[14:15]
	v_pk_mul_f32 v[202:203], v[96:97], v[16:17]
	v_pk_fma_f32 v[14:15], v[140:141], v[14:15], v[200:201] op_sel:[0,1,0] op_sel_hi:[1,0,1] neg_lo:[1,0,0]
	v_pk_fma_f32 v[16:17], v[106:107], v[16:17], v[202:203] op_sel:[0,1,0] op_sel_hi:[1,0,1] neg_lo:[1,0,0]
	v_mfma_f32_16x16x32_bf16 v[18:21], v[22:25], v[70:73], v[18:21]
	v_pk_mul_f32 v[204:205], v[128:129], v[10:11]
	v_pk_mul_f32 v[206:207], v[94:95], v[12:13]
	v_pk_fma_f32 v[10:11], v[138:139], v[10:11], v[204:205] op_sel:[0,1,0] op_sel_hi:[1,0,1] neg_lo:[1,0,0]
	v_pk_fma_f32 v[12:13], v[104:105], v[12:13], v[206:207] op_sel:[0,1,0] op_sel_hi:[1,0,1] neg_lo:[1,0,0]
	v_mfma_f32_16x16x32_bf16 v[14:17], v[38:41], v[70:73], v[14:17]
	v_pk_mul_f32 v[200:201], v[126:127], v[6:7]
	v_pk_mul_f32 v[202:203], v[92:93], v[8:9]
	v_pk_fma_f32 v[6:7], v[136:137], v[6:7], v[200:201] op_sel:[0,1,0] op_sel_hi:[1,0,1] neg_lo:[1,0,0]
	v_pk_fma_f32 v[8:9], v[102:103], v[8:9], v[202:203] op_sel:[0,1,0] op_sel_hi:[1,0,1] neg_lo:[1,0,0]
	v_mfma_f32_16x16x32_bf16 v[10:13], v[42:45], v[70:73], v[10:13]
	v_pk_mul_f32 v[204:205], v[132:133], v[2:3]
	v_pk_mul_f32 v[206:207], v[98:99], v[4:5]
	v_pk_fma_f32 v[2:3], v[134:135], v[2:3], v[204:205] op_sel:[0,1,0] op_sel_hi:[1,0,1] neg_lo:[1,0,0]
	v_pk_fma_f32 v[4:5], v[100:101], v[4:5], v[206:207] op_sel:[0,1,0] op_sel_hi:[1,0,1] neg_lo:[1,0,0]
	v_mfma_f32_16x16x32_bf16 v[6:9], v[46:49], v[70:73], v[6:9]
	s_nop 1
	v_mfma_f32_16x16x32_bf16 v[2:5], v[50:53], v[70:73], v[2:5]
	v_pk_mul_f32 v[200:201], v[154:155], v[62:63]
	v_pk_mul_f32 v[202:203], v[120:121], v[64:65]
	v_pk_fma_f32 v[62:63], v[156:157], v[62:63], v[200:201] op_sel:[0,1,0] op_sel_hi:[1,0,1] neg_lo:[1,0,0]
	v_pk_fma_f32 v[64:65], v[122:123], v[64:65], v[202:203] op_sel:[0,1,0] op_sel_hi:[1,0,1] neg_lo:[1,0,0]
	v_pk_mul_f32 v[204:205], v[150:151], v[58:59]
	v_pk_mul_f32 v[206:207], v[116:117], v[60:61]
	v_pk_fma_f32 v[58:59], v[152:153], v[58:59], v[204:205] op_sel:[0,1,0] op_sel_hi:[1,0,1] neg_lo:[1,0,0]
	v_pk_fma_f32 v[60:61], v[118:119], v[60:61], v[206:207] op_sel:[0,1,0] op_sel_hi:[1,0,1] neg_lo:[1,0,0]
	v_mfma_f32_16x16x32_bf16 v[62:65], v[34:37], v[66:69], v[62:65]
	v_pk_mul_f32 v[200:201], v[146:147], v[54:55]
	v_pk_mul_f32 v[202:203], v[112:113], v[56:57]
	v_pk_fma_f32 v[54:55], v[148:149], v[54:55], v[200:201] op_sel:[0,1,0] op_sel_hi:[1,0,1] neg_lo:[1,0,0]
	v_pk_fma_f32 v[56:57], v[114:115], v[56:57], v[202:203] op_sel:[0,1,0] op_sel_hi:[1,0,1] neg_lo:[1,0,0]
	v_mfma_f32_16x16x32_bf16 v[58:61], v[26:29], v[66:69], v[58:61]
	v_pk_mul_f32 v[204:205], v[142:143], v[18:19]
	v_pk_mul_f32 v[206:207], v[108:109], v[20:21]
	v_pk_fma_f32 v[18:19], v[144:145], v[18:19], v[204:205] op_sel:[0,1,0] op_sel_hi:[1,0,1] neg_lo:[1,0,0]
	v_pk_fma_f32 v[20:21], v[110:111], v[20:21], v[206:207] op_sel:[0,1,0] op_sel_hi:[1,0,1] neg_lo:[1,0,0]
	v_mfma_f32_16x16x32_bf16 v[54:57], v[30:33], v[66:69], v[54:57]
	v_pk_mul_f32 v[200:201], v[130:131], v[14:15]
	v_pk_mul_f32 v[202:203], v[96:97], v[16:17]
	v_pk_fma_f32 v[14:15], v[140:141], v[14:15], v[200:201] op_sel:[0,1,0] op_sel_hi:[1,0,1] neg_lo:[1,0,0]
	v_pk_fma_f32 v[16:17], v[106:107], v[16:17], v[202:203] op_sel:[0,1,0] op_sel_hi:[1,0,1] neg_lo:[1,0,0]
	v_mfma_f32_16x16x32_bf16 v[18:21], v[22:25], v[66:69], v[18:21]
	v_pk_mul_f32 v[204:205], v[128:129], v[10:11]
	v_pk_mul_f32 v[206:207], v[94:95], v[12:13]
	v_pk_fma_f32 v[10:11], v[138:139], v[10:11], v[204:205] op_sel:[0,1,0] op_sel_hi:[1,0,1] neg_lo:[1,0,0]
	v_pk_fma_f32 v[12:13], v[104:105], v[12:13], v[206:207] op_sel:[0,1,0] op_sel_hi:[1,0,1] neg_lo:[1,0,0]
	v_mfma_f32_16x16x32_bf16 v[14:17], v[38:41], v[66:69], v[14:17]
	v_pk_mul_f32 v[200:201], v[126:127], v[6:7]
	v_pk_mul_f32 v[202:203], v[92:93], v[8:9]
	v_pk_fma_f32 v[6:7], v[136:137], v[6:7], v[200:201] op_sel:[0,1,0] op_sel_hi:[1,0,1] neg_lo:[1,0,0]
	v_pk_fma_f32 v[8:9], v[102:103], v[8:9], v[202:203] op_sel:[0,1,0] op_sel_hi:[1,0,1] neg_lo:[1,0,0]
	v_mfma_f32_16x16x32_bf16 v[10:13], v[42:45], v[66:69], v[10:13]
	v_pk_mul_f32 v[204:205], v[132:133], v[2:3]
	v_pk_mul_f32 v[206:207], v[98:99], v[4:5]
	v_pk_fma_f32 v[2:3], v[134:135], v[2:3], v[204:205] op_sel:[0,1,0] op_sel_hi:[1,0,1] neg_lo:[1,0,0]
	v_pk_fma_f32 v[4:5], v[100:101], v[4:5], v[206:207] op_sel:[0,1,0] op_sel_hi:[1,0,1] neg_lo:[1,0,0]
	v_mfma_f32_16x16x32_bf16 v[6:9], v[46:49], v[66:69], v[6:9]
	s_nop 1
	v_mfma_f32_16x16x32_bf16 v[2:5], v[50:53], v[66:69], v[2:5]
	s_cbranch_scc1 .LBB0_381
	global_load_dwordx2 v[32:33], v[90:91], off
	v_add_co_u32_e32 v22, vcc, 0x4000, v90
	s_waitcnt vmcnt(0)
	v_add_f32_e32 v38, v32, v32
	v_addc_co_u32_e32 v23, vcc, 0, v91, vcc
	global_load_dwordx2 v[36:37], v[22:23], off
	global_load_dwordx2 v[24:25], v[22:23], off offset:32
	global_load_dwordx2 v[26:27], v[90:91], off offset:32
	global_load_dwordx2 v[34:35], v[90:91], off offset:64
	global_load_dwordx2 v[28:29], v[90:91], off offset:96
	global_load_dwordx2 v[42:43], v[22:23], off offset:64
	global_load_dwordx2 v[30:31], v[22:23], off offset:96
	v_add_f32_e32 v39, v33, v33
	s_waitcnt vmcnt(6)
	v_fmamk_f32 v40, v36, 0x80000000, v32
	v_fma_f32 v41, 0, v32, v36
	v_mul_f32_e32 v44, v36, v36
	v_mul_f32_e32 v36, v38, v36
	v_fmamk_f32 v38, v37, 0x80000000, v33
	v_fma_f32 v45, 0, v33, v37
	v_mul_f32_e32 v46, v37, v37
	v_mul_f32_e32 v37, v39, v37
	v_cndmask_b32_e64 v40, 1.0, v40, s[10:11]
	v_cndmask_b32_e64 v38, 1.0, v38, s[10:11]
	v_cndmask_b32_e64 v41, 0, v41, s[10:11]
	v_fma_f32 v32, v32, v32, -v44
	v_cndmask_b32_e64 v45, 0, v45, s[10:11]
	v_fma_f32 v33, v33, v33, -v46
	v_mul_f32_e32 v50, v36, v40
	v_mul_f32_e32 v53, v37, v38
	v_mul_f32_e32 v44, v36, v36
	v_mul_f32_e32 v46, v37, v37
	v_mul_f32_e32 v49, v36, v41
	v_add_f32_e32 v51, v32, v32
	v_mul_f32_e32 v52, v37, v45
	v_add_f32_e32 v66, v33, v33
	v_fmac_f32_e32 v50, v32, v41
	v_fmac_f32_e32 v53, v33, v45
	v_fma_f32 v44, v32, v32, -v44
	v_fma_f32 v46, v33, v33, -v46
	v_fma_f32 v49, v32, v40, -v49
	v_mul_f32_e32 v32, v36, v51
	v_fma_f32 v51, v33, v38, -v52
	v_mul_f32_e32 v33, v37, v66
	v_cndmask_b32_e64 v41, v41, v50, s[4:5]
	v_cndmask_b32_e64 v45, v45, v53, s[4:5]
	v_add_f32_e32 v36, v44, v44
	v_cndmask_b32_e64 v40, v40, v49, s[4:5]
	v_mul_f32_e32 v49, v32, v32
	v_cndmask_b32_e64 v38, v38, v51, s[4:5]
	v_mul_f32_e32 v51, v32, v41
	v_mul_f32_e32 v52, v44, v41
	v_mul_f32_e32 v53, v33, v45
	v_mul_f32_e32 v66, v46, v45
	v_add_f32_e32 v37, v46, v46
	v_mul_f32_e32 v36, v32, v36
	v_mul_f32_e32 v50, v33, v33
	v_fma_f32 v49, v44, v44, -v49
	v_fma_f32 v44, v44, v40, -v51
	v_fmac_f32_e32 v52, v32, v40
	v_fma_f32 v32, v46, v38, -v53
	v_fmac_f32_e32 v66, v33, v38
	v_mul_f32_e32 v37, v33, v37
	v_fma_f32 v50, v46, v46, -v50
	v_cndmask_b32_e64 v33, v40, v44, s[6:7]
	v_cndmask_b32_e64 v40, v41, v52, s[6:7]
	v_cndmask_b32_e64 v32, v38, v32, s[6:7]
	v_cndmask_b32_e64 v38, v45, v66, s[6:7]
	v_mul_f32_e32 v41, v36, v40
	v_mul_f32_e32 v44, v49, v40
	v_mul_f32_e32 v45, v37, v38
	v_mul_f32_e32 v46, v50, v38
	s_waitcnt vmcnt(5)
	v_mul_f32_e32 v48, v24, v24
	v_fma_f32 v41, v49, v33, -v41
	v_fmac_f32_e32 v44, v36, v33
	v_fma_f32 v36, v50, v32, -v45
	v_fmac_f32_e32 v46, v37, v32
	s_waitcnt vmcnt(4)
	v_fmamk_f32 v39, v24, 0x80000000, v26
	v_fma_f32 v47, 0, v26, v24
	v_fma_f32 v48, v26, v26, -v48
	v_cndmask_b32_e64 v41, v33, v41, s[8:9]
	v_cndmask_b32_e64 v33, v40, v44, s[8:9]
	v_cndmask_b32_e64 v40, v32, v36, s[8:9]
	v_cndmask_b32_e64 v36, v38, v46, s[8:9]
	v_add_f32_e32 v26, v26, v26
	v_cndmask_b32_e64 v39, 1.0, v39, s[10:11]
	v_cndmask_b32_e64 v47, 0, v47, s[10:11]
	v_mul_f32_e32 v38, v65, v36
	v_mul_f32_e32 v24, v26, v24
	v_mul_f32_e32 v37, v63, v33
	v_mul_f32_e32 v32, v62, v33
	v_mul_f32_e32 v33, v64, v36
	v_fma_f32 v36, v64, v40, -v38
	v_mul_f32_e32 v26, v24, v47
	v_mul_f32_e32 v38, v24, v39
	v_fmac_f32_e32 v33, v65, v40
	v_fma_f32 v26, v48, v39, -v26
	v_fmac_f32_e32 v38, v48, v47
	v_add_f32_e32 v40, v48, v48
	v_cndmask_b32_e64 v26, v39, v26, s[4:5]
	v_cndmask_b32_e64 v38, v47, v38, s[4:5]
	v_mul_f32_e32 v39, v24, v24
	v_mul_f32_e32 v24, v24, v40
	v_fma_f32 v39, v48, v48, -v39
	v_mul_f32_e32 v40, v24, v38
	v_fma_f32 v37, v62, v41, -v37
	v_fmac_f32_e32 v32, v63, v41
	v_fma_f32 v40, v39, v26, -v40
	v_mul_f32_e32 v41, v39, v38
	v_fmac_f32_e32 v41, v24, v26
	v_cndmask_b32_e64 v26, v26, v40, s[6:7]
	v_mul_f32_e32 v40, v24, v24
	v_fma_f32 v40, v39, v39, -v40
	v_add_f32_e32 v39, v39, v39
	v_cndmask_b32_e64 v38, v38, v41, s[6:7]
	v_mul_f32_e32 v24, v24, v39
	v_mul_f32_e32 v39, v24, v38
	v_fma_f32 v39, v40, v26, -v39
	v_mul_f32_e32 v40, v40, v38
	v_fmac_f32_e32 v40, v24, v26
	v_cndmask_b32_e64 v24, v26, v39, s[8:9]
	v_cndmask_b32_e64 v26, v38, v40, s[8:9]
	v_mul_f32_e32 v38, v59, v26
	v_mul_f32_e32 v39, v58, v26
	v_mul_f32_e32 v40, v25, v25
	v_fma_f32 v38, v58, v24, -v38
	v_fmac_f32_e32 v39, v59, v24
	v_fmamk_f32 v24, v25, 0x80000000, v27
	v_fma_f32 v26, 0, v27, v25
	v_fma_f32 v40, v27, v27, -v40
	v_add_f32_e32 v27, v27, v27
	v_cndmask_b32_e64 v26, 0, v26, s[10:11]
	v_mul_f32_e32 v25, v27, v25
	v_cndmask_b32_e64 v24, 1.0, v24, s[10:11]
	v_mul_f32_e32 v27, v25, v26
	v_fma_f32 v27, v40, v24, -v27
	v_mul_f32_e32 v41, v25, v24
	v_cndmask_b32_e64 v24, v24, v27, s[4:5]
	v_mul_f32_e32 v27, v25, v25
	v_fmac_f32_e32 v41, v40, v26
	v_fma_f32 v27, v40, v40, -v27
	v_add_f32_e32 v40, v40, v40
	v_cndmask_b32_e64 v26, v26, v41, s[4:5]
	v_mul_f32_e32 v25, v25, v40
	v_mul_f32_e32 v40, v25, v26
	v_fma_f32 v40, v27, v24, -v40
	v_mul_f32_e32 v41, v27, v26
	v_fmac_f32_e32 v41, v25, v24
	v_cndmask_b32_e64 v24, v24, v40, s[6:7]
	v_mul_f32_e32 v40, v25, v25
	v_fma_f32 v40, v27, v27, -v40
	v_add_f32_e32 v27, v27, v27
	v_cndmask_b32_e64 v26, v26, v41, s[6:7]
	v_mul_f32_e32 v25, v25, v27
	v_mul_f32_e32 v27, v25, v26
	v_fma_f32 v27, v40, v24, -v27
	v_mul_f32_e32 v40, v40, v26
	v_fmac_f32_e32 v40, v25, v24
	v_cndmask_b32_e64 v25, v26, v40, s[8:9]
	v_cndmask_b32_e64 v24, v24, v27, s[8:9]
	v_mul_f32_e32 v26, v61, v25
	v_mul_f32_e32 v41, v60, v25
	s_waitcnt vmcnt(1)
	v_fma_f32 v25, 0, v34, v42
	v_add_f32_e32 v27, v34, v34
	v_fma_f32 v40, v60, v24, -v26
	v_fmac_f32_e32 v41, v61, v24
	v_fmamk_f32 v24, v42, 0x80000000, v34
	v_cndmask_b32_e64 v25, 0, v25, s[10:11]
	v_mul_f32_e32 v26, v42, v42
	v_mul_f32_e32 v27, v27, v42
	v_cndmask_b32_e64 v24, 1.0, v24, s[10:11]
	v_fma_f32 v26, v34, v34, -v26
	v_mul_f32_e32 v34, v27, v25
	v_fma_f32 v34, v26, v24, -v34
	v_mul_f32_e32 v42, v27, v24
	v_cndmask_b32_e64 v24, v24, v34, s[4:5]
	v_mul_f32_e32 v34, v27, v27
	v_fmac_f32_e32 v42, v26, v25
	v_fma_f32 v34, v26, v26, -v34
	v_add_f32_e32 v26, v26, v26
	v_cndmask_b32_e64 v25, v25, v42, s[4:5]
	v_mul_f32_e32 v26, v27, v26
	v_mul_f32_e32 v27, v26, v25
	v_fma_f32 v27, v34, v24, -v27
	v_mul_f32_e32 v42, v34, v25
	v_fmac_f32_e32 v42, v26, v24
	v_cndmask_b32_e64 v24, v24, v27, s[6:7]
	v_mul_f32_e32 v27, v26, v26
	v_fma_f32 v27, v34, v34, -v27
	v_add_f32_e32 v34, v34, v34
	v_cndmask_b32_e64 v25, v25, v42, s[6:7]
	v_mul_f32_e32 v26, v26, v34
	v_mul_f32_e32 v34, v26, v25
	v_fma_f32 v34, v27, v24, -v34
	v_mul_f32_e32 v27, v27, v25
	v_fmac_f32_e32 v27, v26, v24
	v_cndmask_b32_e64 v25, v25, v27, s[8:9]
	v_cndmask_b32_e64 v24, v24, v34, s[8:9]
	v_mul_f32_e32 v26, v55, v25
	v_mul_f32_e32 v42, v54, v25
	v_fma_f32 v25, 0, v35, v43
	v_add_f32_e32 v27, v35, v35
	v_fma_f32 v34, v54, v24, -v26
	v_fmac_f32_e32 v42, v55, v24
	v_fmamk_f32 v24, v43, 0x80000000, v35
	v_cndmask_b32_e64 v25, 0, v25, s[10:11]
	v_mul_f32_e32 v26, v43, v43
	v_mul_f32_e32 v27, v27, v43
	v_cndmask_b32_e64 v24, 1.0, v24, s[10:11]
	v_fma_f32 v26, v35, v35, -v26
	v_mul_f32_e32 v35, v27, v25
	v_fma_f32 v35, v26, v24, -v35
	v_mul_f32_e32 v43, v27, v24
	v_cndmask_b32_e64 v24, v24, v35, s[4:5]
	v_mul_f32_e32 v35, v27, v27
	v_fmac_f32_e32 v43, v26, v25
	v_fma_f32 v35, v26, v26, -v35
	v_add_f32_e32 v26, v26, v26
	v_cndmask_b32_e64 v25, v25, v43, s[4:5]
	v_mul_f32_e32 v26, v27, v26
	v_mul_f32_e32 v27, v26, v25
	v_fma_f32 v27, v35, v24, -v27
	v_mul_f32_e32 v43, v35, v25
	v_fmac_f32_e32 v43, v26, v24
	v_cndmask_b32_e64 v24, v24, v27, s[6:7]
	v_mul_f32_e32 v27, v26, v26
	v_fma_f32 v27, v35, v35, -v27
	v_add_f32_e32 v35, v35, v35
	v_cndmask_b32_e64 v25, v25, v43, s[6:7]
	v_mul_f32_e32 v26, v26, v35
	v_mul_f32_e32 v35, v26, v25
	v_fma_f32 v35, v27, v24, -v35
	v_mul_f32_e32 v27, v27, v25
	v_fmac_f32_e32 v27, v26, v24
	v_cndmask_b32_e64 v25, v25, v27, s[8:9]
	v_cndmask_b32_e64 v24, v24, v35, s[8:9]
	v_mul_f32_e32 v26, v57, v25
	v_mul_f32_e32 v35, v56, v25
	v_fma_f32 v43, v56, v24, -v26
	v_fmac_f32_e32 v35, v57, v24
	s_waitcnt vmcnt(0)
	v_fmamk_f32 v24, v30, 0x80000000, v28
	v_cndmask_b32_e64 v45, 1.0, v24, s[10:11]
	global_load_dwordx2 v[24:25], v[90:91], off offset:128
	global_load_dwordx2 v[26:27], v[22:23], off offset:128
	v_mul_f32_e32 v46, v30, v30
	v_fma_f32 v44, 0, v28, v30
	v_fma_f32 v46, v28, v28, -v46
	v_add_f32_e32 v28, v28, v28
	v_cndmask_b32_e64 v44, 0, v44, s[10:11]
	v_mul_f32_e32 v28, v28, v30
	v_mul_f32_e32 v30, v28, v44
	v_fma_f32 v30, v46, v45, -v30
	v_mul_f32_e32 v47, v28, v45
	v_cndmask_b32_e64 v30, v45, v30, s[4:5]
	v_mul_f32_e32 v45, v28, v28
	v_fmac_f32_e32 v47, v46, v44
	v_fma_f32 v45, v46, v46, -v45
	v_add_f32_e32 v46, v46, v46
	v_cndmask_b32_e64 v44, v44, v47, s[4:5]
	v_mul_f32_e32 v28, v28, v46
	v_mul_f32_e32 v46, v28, v44
	v_fma_f32 v46, v45, v30, -v46
	v_mul_f32_e32 v47, v45, v44
	v_fmac_f32_e32 v47, v28, v30
	v_cndmask_b32_e64 v30, v30, v46, s[6:7]
	v_mul_f32_e32 v46, v28, v28
	v_fma_f32 v46, v45, v45, -v46
	v_add_f32_e32 v45, v45, v45
	v_cndmask_b32_e64 v44, v44, v47, s[6:7]
	v_mul_f32_e32 v28, v28, v45
	v_mul_f32_e32 v45, v28, v44
	v_fma_f32 v45, v46, v30, -v45
	v_mul_f32_e32 v46, v46, v44
	v_fmac_f32_e32 v46, v28, v30
	v_cndmask_b32_e64 v28, v30, v45, s[8:9]
	v_cndmask_b32_e64 v30, v44, v46, s[8:9]
	v_mul_f32_e32 v44, v19, v30
	v_mul_f32_e32 v45, v18, v30
	v_fma_f32 v44, v18, v28, -v44
	v_fmac_f32_e32 v45, v19, v28
	v_mul_f32_e32 v28, v31, v31
	v_fmamk_f32 v18, v31, 0x80000000, v29
	v_fma_f32 v19, 0, v29, v31
	v_fma_f32 v28, v29, v29, -v28
	v_add_f32_e32 v29, v29, v29
	v_cndmask_b32_e64 v19, 0, v19, s[10:11]
	v_mul_f32_e32 v29, v29, v31
	v_cndmask_b32_e64 v18, 1.0, v18, s[10:11]
	v_mul_f32_e32 v30, v29, v19
	v_fma_f32 v30, v28, v18, -v30
	v_mul_f32_e32 v31, v29, v18
	v_cndmask_b32_e64 v18, v18, v30, s[4:5]
	v_mul_f32_e32 v30, v29, v29
	v_fmac_f32_e32 v31, v28, v19
	v_fma_f32 v30, v28, v28, -v30
	v_add_f32_e32 v28, v28, v28
	v_cndmask_b32_e64 v19, v19, v31, s[4:5]
	v_mul_f32_e32 v28, v29, v28
	v_mul_f32_e32 v29, v28, v19
	v_fma_f32 v29, v30, v18, -v29
	v_mul_f32_e32 v31, v30, v19
	v_fmac_f32_e32 v31, v28, v18
	v_cndmask_b32_e64 v18, v18, v29, s[6:7]
	v_mul_f32_e32 v29, v28, v28
	v_fma_f32 v29, v30, v30, -v29
	v_add_f32_e32 v30, v30, v30
	v_cndmask_b32_e64 v19, v19, v31, s[6:7]
	v_mul_f32_e32 v28, v28, v30
	v_mul_f32_e32 v30, v28, v19
	v_fma_f32 v30, v29, v18, -v30
	v_mul_f32_e32 v29, v29, v19
	v_fmac_f32_e32 v29, v28, v18
	v_cndmask_b32_e64 v19, v19, v29, s[8:9]
	v_cndmask_b32_e64 v18, v18, v30, s[8:9]
	v_mul_f32_e32 v28, v21, v19
	v_mul_f32_e32 v47, v20, v19
	v_fma_f32 v46, v20, v18, -v28
	v_fmac_f32_e32 v47, v21, v18
	global_load_dwordx2 v[18:19], v[22:23], off offset:160
	global_load_dwordx2 v[20:21], v[90:91], off offset:160
	global_load_dwordx2 v[28:29], v[90:91], off offset:192
	global_load_dwordx2 v[30:31], v[90:91], off offset:224
	global_load_dwordx2 v[48:49], v[22:23], off offset:192
	s_nop 0
	global_load_dwordx2 v[22:23], v[22:23], off offset:224
	s_waitcnt vmcnt(6)
	v_mul_f32_e32 v52, v26, v26
	v_fmamk_f32 v50, v26, 0x80000000, v24
	v_fma_f32 v51, 0, v24, v26
	v_fma_f32 v52, v24, v24, -v52
	v_add_f32_e32 v24, v24, v24
	v_cndmask_b32_e64 v50, 1.0, v50, s[10:11]
	v_cndmask_b32_e64 v51, 0, v51, s[10:11]
	v_mul_f32_e32 v24, v24, v26
	v_mul_f32_e32 v26, v24, v51
	v_mul_f32_e32 v53, v24, v50
	v_fma_f32 v26, v52, v50, -v26
	v_fmac_f32_e32 v53, v52, v51
	v_cndmask_b32_e64 v26, v50, v26, s[4:5]
	v_cndmask_b32_e64 v50, v51, v53, s[4:5]
	v_mul_f32_e32 v51, v24, v24
	v_fma_f32 v51, v52, v52, -v51
	v_add_f32_e32 v52, v52, v52
	v_mul_f32_e32 v24, v24, v52
	v_mul_f32_e32 v52, v24, v50
	v_fma_f32 v52, v51, v26, -v52
	v_mul_f32_e32 v53, v51, v50
	v_fmac_f32_e32 v53, v24, v26
	v_cndmask_b32_e64 v26, v26, v52, s[6:7]
	v_mul_f32_e32 v52, v24, v24
	v_fma_f32 v52, v51, v51, -v52
	v_add_f32_e32 v51, v51, v51
	v_cndmask_b32_e64 v50, v50, v53, s[6:7]
	v_mul_f32_e32 v24, v24, v51
	v_mul_f32_e32 v51, v24, v50
	v_fma_f32 v51, v52, v26, -v51
	v_mul_f32_e32 v52, v52, v50
	v_fmac_f32_e32 v52, v24, v26
	v_cndmask_b32_e64 v24, v26, v51, s[8:9]
	v_cndmask_b32_e64 v26, v50, v52, s[8:9]
	v_mul_f32_e32 v50, v15, v26
	v_fma_f32 v50, v14, v24, -v50
	v_mul_f32_e32 v14, v14, v26
	v_mul_f32_e32 v26, v27, v27
	v_fmac_f32_e32 v14, v15, v24
	v_fmamk_f32 v15, v27, 0x80000000, v25
	v_fma_f32 v24, 0, v25, v27
	v_fma_f32 v26, v25, v25, -v26
	v_add_f32_e32 v25, v25, v25
	v_cndmask_b32_e64 v24, 0, v24, s[10:11]
	v_mul_f32_e32 v25, v25, v27
	v_cndmask_b32_e64 v15, 1.0, v15, s[10:11]
	v_mul_f32_e32 v27, v25, v24
	v_fma_f32 v27, v26, v15, -v27
	v_mul_f32_e32 v51, v25, v15
	v_cndmask_b32_e64 v15, v15, v27, s[4:5]
	v_mul_f32_e32 v27, v25, v25
	v_fmac_f32_e32 v51, v26, v24
	v_fma_f32 v27, v26, v26, -v27
	v_add_f32_e32 v26, v26, v26
	v_cndmask_b32_e64 v24, v24, v51, s[4:5]
	v_mul_f32_e32 v25, v25, v26
	v_mul_f32_e32 v26, v25, v24
	v_fma_f32 v26, v27, v15, -v26
	v_mul_f32_e32 v51, v27, v24
	v_fmac_f32_e32 v51, v25, v15
	v_cndmask_b32_e64 v15, v15, v26, s[6:7]
	v_mul_f32_e32 v26, v25, v25
	v_fma_f32 v26, v27, v27, -v26
	v_add_f32_e32 v27, v27, v27
	v_cndmask_b32_e64 v24, v24, v51, s[6:7]
	v_mul_f32_e32 v25, v25, v27
	v_mul_f32_e32 v27, v25, v24
	v_fma_f32 v27, v26, v15, -v27
	v_mul_f32_e32 v26, v26, v24
	v_fmac_f32_e32 v26, v25, v15
	v_cndmask_b32_e64 v24, v24, v26, s[8:9]
	v_cndmask_b32_e64 v15, v15, v27, s[8:9]
	v_mul_f32_e32 v25, v17, v24
	v_fma_f32 v25, v16, v15, -v25
	v_mul_f32_e32 v16, v16, v24
	s_waitcnt vmcnt(5)
	v_mul_f32_e32 v24, v18, v18
	v_fmac_f32_e32 v16, v17, v15
	s_waitcnt vmcnt(4)
	v_fmamk_f32 v15, v18, 0x80000000, v20
	v_fma_f32 v17, 0, v20, v18
	v_fma_f32 v24, v20, v20, -v24
	v_add_f32_e32 v20, v20, v20
	v_cndmask_b32_e64 v17, 0, v17, s[10:11]
	v_mul_f32_e32 v18, v20, v18
	v_cndmask_b32_e64 v15, 1.0, v15, s[10:11]
	v_mul_f32_e32 v20, v18, v17
	v_fma_f32 v20, v24, v15, -v20
	v_mul_f32_e32 v26, v18, v15
	v_cndmask_b32_e64 v15, v15, v20, s[4:5]
	v_mul_f32_e32 v20, v18, v18
	v_fmac_f32_e32 v26, v24, v17
	v_fma_f32 v20, v24, v24, -v20
	v_add_f32_e32 v24, v24, v24
	v_cndmask_b32_e64 v17, v17, v26, s[4:5]
	v_mul_f32_e32 v18, v18, v24
	v_mul_f32_e32 v24, v18, v17
	v_fma_f32 v24, v20, v15, -v24
	v_mul_f32_e32 v26, v20, v17
	v_fmac_f32_e32 v26, v18, v15
	v_cndmask_b32_e64 v15, v15, v24, s[6:7]
	v_mul_f32_e32 v24, v18, v18
	v_fma_f32 v24, v20, v20, -v24
	v_add_f32_e32 v20, v20, v20
	v_cndmask_b32_e64 v17, v17, v26, s[6:7]
	v_mul_f32_e32 v18, v18, v20
	v_mul_f32_e32 v20, v18, v17
	v_fma_f32 v20, v24, v15, -v20
	v_mul_f32_e32 v24, v24, v17
	v_fmac_f32_e32 v24, v18, v15
	v_cndmask_b32_e64 v17, v17, v24, s[8:9]
	v_cndmask_b32_e64 v15, v15, v20, s[8:9]
	v_mul_f32_e32 v18, v11, v17
	v_fma_f32 v18, v10, v15, -v18
	v_mul_f32_e32 v10, v10, v17
	v_fmac_f32_e32 v10, v11, v15
	v_fma_f32 v15, 0, v21, v19
	v_add_f32_e32 v20, v21, v21
	v_fmamk_f32 v11, v19, 0x80000000, v21
	v_cndmask_b32_e64 v15, 0, v15, s[10:11]
	v_mul_f32_e32 v17, v19, v19
	v_mul_f32_e32 v19, v20, v19
	v_cndmask_b32_e64 v11, 1.0, v11, s[10:11]
	v_fma_f32 v17, v21, v21, -v17
	v_mul_f32_e32 v20, v19, v15
	v_fma_f32 v20, v17, v11, -v20
	v_mul_f32_e32 v21, v19, v11
	v_cndmask_b32_e64 v11, v11, v20, s[4:5]
	v_mul_f32_e32 v20, v19, v19
	v_fmac_f32_e32 v21, v17, v15
	v_fma_f32 v20, v17, v17, -v20
	v_add_f32_e32 v17, v17, v17
	v_cndmask_b32_e64 v15, v15, v21, s[4:5]
	v_mul_f32_e32 v17, v19, v17
	v_mul_f32_e32 v19, v17, v15
	v_fma_f32 v19, v20, v11, -v19
	v_mul_f32_e32 v21, v20, v15
	v_fmac_f32_e32 v21, v17, v11
	v_cndmask_b32_e64 v11, v11, v19, s[6:7]
	v_mul_f32_e32 v19, v17, v17
	v_fma_f32 v19, v20, v20, -v19
	v_add_f32_e32 v20, v20, v20
	v_cndmask_b32_e64 v15, v15, v21, s[6:7]
	v_mul_f32_e32 v17, v17, v20
	v_mul_f32_e32 v20, v17, v15
	v_fma_f32 v20, v19, v11, -v20
	v_mul_f32_e32 v19, v19, v15
	v_fmac_f32_e32 v19, v17, v11
	v_cndmask_b32_e64 v15, v15, v19, s[8:9]
	v_cndmask_b32_e64 v11, v11, v20, s[8:9]
	v_mul_f32_e32 v17, v13, v15
	v_fma_f32 v17, v12, v11, -v17
	v_mul_f32_e32 v12, v12, v15
	v_fmac_f32_e32 v12, v13, v11
	s_waitcnt vmcnt(1)
	v_fma_f32 v13, 0, v28, v48
	v_add_f32_e32 v19, v28, v28
	v_fmamk_f32 v11, v48, 0x80000000, v28
	v_cndmask_b32_e64 v13, 0, v13, s[10:11]
	v_mul_f32_e32 v15, v48, v48
	v_mul_f32_e32 v19, v19, v48
	v_cndmask_b32_e64 v11, 1.0, v11, s[10:11]
	v_fma_f32 v15, v28, v28, -v15
	v_mul_f32_e32 v20, v19, v13
	v_fma_f32 v20, v15, v11, -v20
	v_mul_f32_e32 v21, v19, v11
	v_cndmask_b32_e64 v11, v11, v20, s[4:5]
	v_mul_f32_e32 v20, v19, v19
	v_fmac_f32_e32 v21, v15, v13
	v_fma_f32 v20, v15, v15, -v20
	v_add_f32_e32 v15, v15, v15
	v_cndmask_b32_e64 v13, v13, v21, s[4:5]
	v_mul_f32_e32 v15, v19, v15
	v_mul_f32_e32 v19, v15, v13
	v_fma_f32 v19, v20, v11, -v19
	v_mul_f32_e32 v21, v20, v13
	v_fmac_f32_e32 v21, v15, v11
	v_cndmask_b32_e64 v11, v11, v19, s[6:7]
	v_mul_f32_e32 v19, v15, v15
	v_fma_f32 v19, v20, v20, -v19
	v_add_f32_e32 v20, v20, v20
	v_cndmask_b32_e64 v13, v13, v21, s[6:7]
	v_mul_f32_e32 v15, v15, v20
	v_mul_f32_e32 v20, v15, v13
	v_fma_f32 v20, v19, v11, -v20
	v_mul_f32_e32 v19, v19, v13
	v_fmac_f32_e32 v19, v15, v11
	v_cndmask_b32_e64 v13, v13, v19, s[8:9]
	v_cndmask_b32_e64 v11, v11, v20, s[8:9]
	v_mul_f32_e32 v15, v7, v13
	v_fma_f32 v15, v6, v11, -v15
	v_mul_f32_e32 v6, v6, v13
	v_fmac_f32_e32 v6, v7, v11
	v_fma_f32 v11, 0, v29, v49
	v_add_f32_e32 v19, v29, v29
	v_fmamk_f32 v7, v49, 0x80000000, v29
	v_cndmask_b32_e64 v11, 0, v11, s[10:11]
	v_mul_f32_e32 v13, v49, v49
	v_mul_f32_e32 v19, v19, v49
	v_cndmask_b32_e64 v7, 1.0, v7, s[10:11]
	v_fma_f32 v13, v29, v29, -v13
	v_mul_f32_e32 v20, v19, v11
	v_fma_f32 v20, v13, v7, -v20
	v_mul_f32_e32 v21, v19, v7
	v_cndmask_b32_e64 v7, v7, v20, s[4:5]
	v_mul_f32_e32 v20, v19, v19
	v_fmac_f32_e32 v21, v13, v11
	v_fma_f32 v20, v13, v13, -v20
	v_add_f32_e32 v13, v13, v13
	v_cndmask_b32_e64 v11, v11, v21, s[4:5]
	v_mul_f32_e32 v13, v19, v13
	v_mul_f32_e32 v19, v13, v11
	v_fma_f32 v19, v20, v7, -v19
	v_mul_f32_e32 v21, v20, v11
	v_fmac_f32_e32 v21, v13, v7
	v_cndmask_b32_e64 v7, v7, v19, s[6:7]
	v_mul_f32_e32 v19, v13, v13
	v_fma_f32 v19, v20, v20, -v19
	v_add_f32_e32 v20, v20, v20
	v_cndmask_b32_e64 v11, v11, v21, s[6:7]
	v_mul_f32_e32 v13, v13, v20
	v_mul_f32_e32 v20, v13, v11
	v_fma_f32 v20, v19, v7, -v20
	v_mul_f32_e32 v19, v19, v11
	v_fmac_f32_e32 v19, v13, v7
	v_cndmask_b32_e64 v11, v11, v19, s[8:9]
	v_cndmask_b32_e64 v7, v7, v20, s[8:9]
	v_mul_f32_e32 v13, v9, v11
	v_fma_f32 v13, v8, v7, -v13
	v_mul_f32_e32 v8, v8, v11
	v_fmac_f32_e32 v8, v9, v7
	s_waitcnt vmcnt(0)
	v_fma_f32 v9, 0, v30, v22
	v_add_f32_e32 v19, v30, v30
	v_fmamk_f32 v7, v22, 0x80000000, v30
	v_cndmask_b32_e64 v9, 0, v9, s[10:11]
	v_mul_f32_e32 v11, v22, v22
	v_mul_f32_e32 v19, v19, v22
	v_cndmask_b32_e64 v7, 1.0, v7, s[10:11]
	v_fma_f32 v11, v30, v30, -v11
	v_mul_f32_e32 v20, v19, v9
	v_fma_f32 v20, v11, v7, -v20
	v_mul_f32_e32 v21, v19, v7
	v_cndmask_b32_e64 v7, v7, v20, s[4:5]
	v_mul_f32_e32 v20, v19, v19
	v_fmac_f32_e32 v21, v11, v9
	v_fma_f32 v20, v11, v11, -v20
	v_add_f32_e32 v11, v11, v11
	v_cndmask_b32_e64 v9, v9, v21, s[4:5]
	v_mul_f32_e32 v11, v19, v11
	v_mul_f32_e32 v19, v11, v9
	v_fma_f32 v19, v20, v7, -v19
	v_mul_f32_e32 v21, v20, v9
	v_fmac_f32_e32 v21, v11, v7
	v_cndmask_b32_e64 v7, v7, v19, s[6:7]
	v_mul_f32_e32 v19, v11, v11
	v_fma_f32 v19, v20, v20, -v19
	v_add_f32_e32 v20, v20, v20
	v_cndmask_b32_e64 v9, v9, v21, s[6:7]
	v_mul_f32_e32 v11, v11, v20
	v_mul_f32_e32 v20, v11, v9
	v_fma_f32 v20, v19, v7, -v20
	v_mul_f32_e32 v19, v19, v9
	v_fmac_f32_e32 v19, v11, v7
	v_cndmask_b32_e64 v9, v9, v19, s[8:9]
	v_cndmask_b32_e64 v7, v7, v20, s[8:9]
	v_mul_f32_e32 v11, v3, v9
	v_fma_f32 v11, v2, v7, -v11
	v_mul_f32_e32 v2, v2, v9
	v_fmac_f32_e32 v2, v3, v7
	v_fma_f32 v7, 0, v31, v23
	v_add_f32_e32 v19, v31, v31
	v_fmamk_f32 v3, v23, 0x80000000, v31
	v_cndmask_b32_e64 v7, 0, v7, s[10:11]
	v_mul_f32_e32 v9, v23, v23
	v_mul_f32_e32 v19, v19, v23
	v_cndmask_b32_e64 v3, 1.0, v3, s[10:11]
	v_fma_f32 v9, v31, v31, -v9
	v_mul_f32_e32 v20, v19, v7
	v_fma_f32 v20, v9, v3, -v20
	v_mul_f32_e32 v21, v19, v3
	v_cndmask_b32_e64 v3, v3, v20, s[4:5]
	v_mul_f32_e32 v20, v19, v19
	v_fmac_f32_e32 v21, v9, v7
	v_fma_f32 v20, v9, v9, -v20
	v_add_f32_e32 v9, v9, v9
	v_cndmask_b32_e64 v7, v7, v21, s[4:5]
	v_mul_f32_e32 v9, v19, v9
	v_mul_f32_e32 v19, v9, v7
	v_fma_f32 v19, v20, v3, -v19
	v_mul_f32_e32 v21, v20, v7
	v_fmac_f32_e32 v21, v9, v3
	v_cndmask_b32_e64 v3, v3, v19, s[6:7]
	v_mul_f32_e32 v19, v9, v9
	v_fma_f32 v19, v20, v20, -v19
	v_add_f32_e32 v20, v20, v20
	v_cndmask_b32_e64 v7, v7, v21, s[6:7]
	v_mul_f32_e32 v9, v9, v20
	v_mul_f32_e32 v20, v9, v7
	v_fma_f32 v20, v19, v3, -v20
	v_mul_f32_e32 v19, v19, v7
	v_fmac_f32_e32 v19, v9, v3
	v_and_b32_e32 v9, 64, v191
	v_add_u32_e32 v22, 64, v9
	v_xor_b32_e32 v9, 1, v191
	v_cmp_lt_i32_e32 vcc, v9, v22
	v_cndmask_b32_e64 v7, v7, v19, s[8:9]
	v_cndmask_b32_e64 v3, v3, v20, s[8:9]
	v_cndmask_b32_e32 v9, v191, v9, vcc
	v_lshlrev_b32_e32 v9, 2, v9
	v_mul_f32_e32 v20, v5, v7
	v_fma_f32 v20, v4, v3, -v20
	v_mul_f32_e32 v4, v4, v7
	s_nop 1
	v_add_f32_dpp v200, v36, v36 row_ror:4 row_mask:0xf bank_mask:0xf
	s_nop 1
	v_add_f32_dpp v201, v37, v37 row_ror:4 row_mask:0xf bank_mask:0xf
	s_nop 1
	v_add_f32_dpp v202, v38, v38 row_ror:4 row_mask:0xf bank_mask:0xf
	s_nop 1
	v_add_f32_dpp v203, v39, v39 row_ror:4 row_mask:0xf bank_mask:0xf
	v_fmac_f32_e32 v4, v5, v3
	s_nop 1
	v_add_f32_dpp v204, v14, v14 row_ror:4 row_mask:0xf bank_mask:0xf
	s_nop 1
	v_add_f32_dpp v205, v25, v25 row_ror:4 row_mask:0xf bank_mask:0xf
	s_nop 1
	v_add_f32_dpp v206, v16, v16 row_ror:4 row_mask:0xf bank_mask:0xf
	s_nop 1
	v_add_f32_dpp v207, v18, v18 row_ror:4 row_mask:0xf bank_mask:0xf
	s_nop 1
	v_add_f32_dpp v208, v40, v40 row_ror:4 row_mask:0xf bank_mask:0xf
	s_nop 1
	v_add_f32_dpp v209, v10, v10 row_ror:4 row_mask:0xf bank_mask:0xf
	s_nop 1
	v_add_f32_dpp v210, v17, v17 row_ror:4 row_mask:0xf bank_mask:0xf
	s_nop 1
	v_add_f32_dpp v211, v12, v12 row_ror:4 row_mask:0xf bank_mask:0xf
	s_nop 1
	v_add_f32_dpp v212, v15, v15 row_ror:4 row_mask:0xf bank_mask:0xf
	s_nop 1
	v_add_f32_dpp v213, v6, v6 row_ror:4 row_mask:0xf bank_mask:0xf
	s_nop 1
	v_add_f32_dpp v214, v13, v13 row_ror:4 row_mask:0xf bank_mask:0xf
	s_nop 1
	v_add_f32_dpp v215, v32, v32 row_ror:4 row_mask:0xf bank_mask:0xf
	s_nop 1
	v_add_f32_dpp v216, v33, v33 row_ror:4 row_mask:0xf bank_mask:0xf
	s_nop 1
	v_add_f32_dpp v217, v34, v34 row_ror:4 row_mask:0xf bank_mask:0xf
	s_nop 1
	v_add_f32_dpp v218, v35, v35 row_ror:4 row_mask:0xf bank_mask:0xf
	s_nop 1
	v_add_f32_dpp v219, v8, v8 row_ror:4 row_mask:0xf bank_mask:0xf
	s_nop 1
	v_add_f32_dpp v220, v11, v11 row_ror:4 row_mask:0xf bank_mask:0xf
	s_nop 1
	v_add_f32_dpp v221, v2, v2 row_ror:4 row_mask:0xf bank_mask:0xf
	s_nop 1
	v_add_f32_dpp v222, v20, v20 row_ror:4 row_mask:0xf bank_mask:0xf
	v_xor_b32_e32 v36, 2, v191
	s_nop 1
	v_add_f32_dpp v223, v41, v41 row_ror:4 row_mask:0xf bank_mask:0xf
	s_nop 1
	v_add_f32_dpp v224, v42, v42 row_ror:4 row_mask:0xf bank_mask:0xf
	s_nop 1
	v_add_f32_dpp v225, v43, v43 row_ror:4 row_mask:0xf bank_mask:0xf
	s_nop 1
	v_add_f32_dpp v226, v44, v44 row_ror:4 row_mask:0xf bank_mask:0xf
	s_nop 1
	v_add_f32_dpp v227, v45, v45 row_ror:4 row_mask:0xf bank_mask:0xf
	s_nop 1
	v_add_f32_dpp v228, v46, v46 row_ror:4 row_mask:0xf bank_mask:0xf
	s_nop 1
	v_add_f32_dpp v229, v47, v47 row_ror:4 row_mask:0xf bank_mask:0xf
	s_nop 1
	v_add_f32_dpp v230, v50, v50 row_ror:4 row_mask:0xf bank_mask:0xf
	s_nop 1
	v_add_f32_dpp v231, v4, v4 row_ror:4 row_mask:0xf bank_mask:0xf
	v_cmp_lt_i32_e32 vcc, v36, v22
	v_cndmask_b32_e32 v36, v191, v36, vcc
	v_lshlrev_b32_e32 v36, 2, v36
	v_xor_b32_e32 v11, 4, v191
	v_cmp_lt_i32_e32 vcc, v11, v22
	v_cndmask_b32_e32 v11, v191, v11, vcc
	v_lshlrev_b32_e32 v36, 2, v11
	v_xor_b32_e32 v2, 8, v191
	v_cmp_lt_i32_e32 vcc, v2, v22
	v_cndmask_b32_e32 v2, v191, v2, vcc
	v_lshlrev_b32_e32 v2, 2, v2
	v_add_f32_dpp v200, v200, v200 row_ror:2 row_mask:0xf bank_mask:0xf
	v_add_f32_dpp v201, v201, v201 row_ror:2 row_mask:0xf bank_mask:0xf
	v_add_f32_dpp v202, v202, v202 row_ror:2 row_mask:0xf bank_mask:0xf
	v_add_f32_dpp v203, v203, v203 row_ror:2 row_mask:0xf bank_mask:0xf
	v_add_f32_dpp v204, v204, v204 row_ror:2 row_mask:0xf bank_mask:0xf
	v_add_f32_dpp v205, v205, v205 row_ror:2 row_mask:0xf bank_mask:0xf
	v_add_f32_dpp v206, v206, v206 row_ror:2 row_mask:0xf bank_mask:0xf
	v_add_f32_dpp v207, v207, v207 row_ror:2 row_mask:0xf bank_mask:0xf
	v_add_f32_dpp v208, v208, v208 row_ror:2 row_mask:0xf bank_mask:0xf
	v_add_f32_dpp v209, v209, v209 row_ror:2 row_mask:0xf bank_mask:0xf
	v_add_f32_dpp v210, v210, v210 row_ror:2 row_mask:0xf bank_mask:0xf
	v_add_f32_dpp v211, v211, v211 row_ror:2 row_mask:0xf bank_mask:0xf
	v_add_f32_dpp v212, v212, v212 row_ror:2 row_mask:0xf bank_mask:0xf
	v_add_f32_dpp v213, v213, v213 row_ror:2 row_mask:0xf bank_mask:0xf
	v_add_f32_dpp v214, v214, v214 row_ror:2 row_mask:0xf bank_mask:0xf
	v_add_f32_dpp v215, v215, v215 row_ror:2 row_mask:0xf bank_mask:0xf
	v_add_f32_dpp v216, v216, v216 row_ror:2 row_mask:0xf bank_mask:0xf
	v_add_f32_dpp v217, v217, v217 row_ror:2 row_mask:0xf bank_mask:0xf
	v_add_f32_dpp v218, v218, v218 row_ror:2 row_mask:0xf bank_mask:0xf
	v_add_f32_dpp v219, v219, v219 row_ror:2 row_mask:0xf bank_mask:0xf
	v_add_f32_dpp v220, v220, v220 row_ror:2 row_mask:0xf bank_mask:0xf
	v_add_f32_dpp v221, v221, v221 row_ror:2 row_mask:0xf bank_mask:0xf
	v_add_f32_dpp v222, v222, v222 row_ror:2 row_mask:0xf bank_mask:0xf
	v_add_f32_dpp v223, v223, v223 row_ror:2 row_mask:0xf bank_mask:0xf
	v_add_f32_dpp v224, v224, v224 row_ror:2 row_mask:0xf bank_mask:0xf
	v_add_f32_dpp v225, v225, v225 row_ror:2 row_mask:0xf bank_mask:0xf
	v_add_f32_dpp v226, v226, v226 row_ror:2 row_mask:0xf bank_mask:0xf
	v_add_f32_dpp v227, v227, v227 row_ror:2 row_mask:0xf bank_mask:0xf
	v_add_f32_dpp v228, v228, v228 row_ror:2 row_mask:0xf bank_mask:0xf
	v_add_f32_dpp v229, v229, v229 row_ror:2 row_mask:0xf bank_mask:0xf
	v_add_f32_dpp v230, v230, v230 row_ror:2 row_mask:0xf bank_mask:0xf
	v_add_f32_dpp v231, v231, v231 row_ror:2 row_mask:0xf bank_mask:0xf
	v_add_f32_dpp v7, v200, v200 row_ror:1 row_mask:0xf bank_mask:0xf
	v_add_f32_dpp v9, v201, v201 row_ror:1 row_mask:0xf bank_mask:0xf
	v_add_f32_dpp v11, v202, v202 row_ror:1 row_mask:0xf bank_mask:0xf
	v_add_f32_dpp v12, v203, v203 row_ror:1 row_mask:0xf bank_mask:0xf
	v_add_f32_dpp v24, v204, v204 row_ror:1 row_mask:0xf bank_mask:0xf
	v_add_f32_dpp v30, v205, v205 row_ror:1 row_mask:0xf bank_mask:0xf
	v_add_f32_dpp v31, v206, v206 row_ror:1 row_mask:0xf bank_mask:0xf
	v_add_f32_dpp v33, v207, v207 row_ror:1 row_mask:0xf bank_mask:0xf
	v_add_f32_dpp v13, v208, v208 row_ror:1 row_mask:0xf bank_mask:0xf
	v_add_f32_dpp v34, v209, v209 row_ror:1 row_mask:0xf bank_mask:0xf
	v_add_f32_dpp v42, v210, v210 row_ror:1 row_mask:0xf bank_mask:0xf
	v_add_f32_dpp v46, v211, v211 row_ror:1 row_mask:0xf bank_mask:0xf
	v_add_f32_dpp v40, v212, v212 row_ror:1 row_mask:0xf bank_mask:0xf
	v_add_f32_dpp v39, v213, v213 row_ror:1 row_mask:0xf bank_mask:0xf
	v_add_f32_dpp v49, v214, v214 row_ror:1 row_mask:0xf bank_mask:0xf
	v_add_f32_dpp v10, v215, v215 row_ror:1 row_mask:0xf bank_mask:0xf
	v_add_f32_dpp v8, v216, v216 row_ror:1 row_mask:0xf bank_mask:0xf
	v_add_f32_dpp v15, v217, v217 row_ror:1 row_mask:0xf bank_mask:0xf
	v_add_f32_dpp v18, v218, v218 row_ror:1 row_mask:0xf bank_mask:0xf
	v_add_f32_dpp v52, v219, v219 row_ror:1 row_mask:0xf bank_mask:0xf
	v_add_f32_dpp v58, v220, v220 row_ror:1 row_mask:0xf bank_mask:0xf
	v_add_f32_dpp v57, v221, v221 row_ror:1 row_mask:0xf bank_mask:0xf
	v_add_f32_dpp v62, v222, v222 row_ror:1 row_mask:0xf bank_mask:0xf
	v_add_f32_dpp v16, v223, v223 row_ror:1 row_mask:0xf bank_mask:0xf
	v_add_f32_dpp v14, v224, v224 row_ror:1 row_mask:0xf bank_mask:0xf
	v_add_f32_dpp v17, v225, v225 row_ror:1 row_mask:0xf bank_mask:0xf
	v_add_f32_dpp v20, v226, v226 row_ror:1 row_mask:0xf bank_mask:0xf
	v_add_f32_dpp v21, v227, v227 row_ror:1 row_mask:0xf bank_mask:0xf
	v_add_f32_dpp v27, v228, v228 row_ror:1 row_mask:0xf bank_mask:0xf
	v_add_f32_dpp v28, v229, v229 row_ror:1 row_mask:0xf bank_mask:0xf
	v_add_f32_dpp v19, v230, v230 row_ror:1 row_mask:0xf bank_mask:0xf
	v_add_f32_dpp v63, v231, v231 row_ror:1 row_mask:0xf bank_mask:0xf
	ds_bpermute_b32 v25, v2, v9
	ds_bpermute_b32 v26, v2, v10
	ds_bpermute_b32 v22, v2, v7
	ds_bpermute_b32 v23, v2, v8
	ds_bpermute_b32 v29, v2, v11
	ds_bpermute_b32 v32, v2, v12
	ds_bpermute_b32 v37, v2, v13
	ds_bpermute_b32 v38, v2, v16
	ds_bpermute_b32 v36, v2, v15
	ds_bpermute_b32 v35, v2, v14
	ds_bpermute_b32 v44, v2, v17
	ds_bpermute_b32 v45, v2, v18
	ds_bpermute_b32 v47, v2, v20
	ds_bpermute_b32 v48, v2, v21
	ds_bpermute_b32 v53, v2, v27
	ds_bpermute_b32 v54, v2, v28
	ds_bpermute_b32 v43, v2, v19
	ds_bpermute_b32 v41, v2, v24
	ds_bpermute_b32 v50, v2, v30
	ds_bpermute_b32 v51, v2, v31
	ds_bpermute_b32 v55, v2, v33
	ds_bpermute_b32 v56, v2, v34
	ds_bpermute_b32 v61, v2, v42
	ds_bpermute_b32 v64, v2, v46
	ds_bpermute_b32 v60, v2, v40
	ds_bpermute_b32 v59, v2, v39
	ds_bpermute_b32 v66, v2, v49
	ds_bpermute_b32 v65, v2, v52
	ds_bpermute_b32 v68, v2, v58
	ds_bpermute_b32 v67, v2, v57
	ds_bpermute_b32 v69, v2, v62
	ds_bpermute_b32 v70, v2, v63
	v_lshlrev_b32_e32 v2, 4, v193
	v_and_b32_e32 v3, 0xfffffc00, v192
	v_or3_b32 v2, v2, v3, v87
	v_ashrrev_i32_e32 v3, 31, v2
	v_lshlrev_b64 v[2:3], 9, v[2:3]
	v_lshl_add_u64 v[2:3], s[38:39], 0, v[2:3]
	v_lshl_add_u64 v[2:3], v[2:3], 0, v[84:85]
	v_lshl_add_u64 v[2:3], v[2:3], 0, s[36:37]
	v_cmp_lt_i32_e32 vcc, 7, v82
	s_and_saveexec_b64 s[0:1], vcc
	s_xor_b64 s[0:1], exec, s[0:1]
	s_cbranch_execz .LBB0_412
	v_cmp_lt_i32_e32 vcc, 11, v82
	s_and_saveexec_b64 s[12:13], vcc
	s_xor_b64 s[12:13], exec, s[12:13]
	s_cbranch_execz .LBB0_397
	v_cmp_lt_i32_e32 vcc, 13, v82
	s_and_saveexec_b64 s[38:39], vcc
	s_xor_b64 s[38:39], exec, s[38:39]
	s_cbranch_execz .LBB0_390
	v_cmp_lt_i32_e32 vcc, 14, v82
	s_and_saveexec_b64 s[40:41], vcc
	s_xor_b64 s[40:41], exec, s[40:41]
	s_cbranch_execz .LBB0_387
	s_waitcnt lgkmcnt(1)
	v_add_f32_e32 v4, v62, v69
	s_waitcnt lgkmcnt(0)
	v_add_f32_e32 v6, v63, v70
	global_store_dword v[2:3], v4, off offset:228 sc0 sc1
